# MLA blocks: scalar compares and one row-sum add moved from between MFMAs to in front of the chains' LDS waits (zero byte change)
# speedup vs baseline: 1.0039x; 1.0039x over previous
; #define LAS __attribute__((address_space(3)))
; #define MFMA32(a, b, c) __builtin_amdgcn_mfma_f32_32x32x16_bf16((a), (b), (c), 0, 0, 0)
; template <int DQK, int DV, bool CAUSAL, int KT, bool PRIO>
; DI void attn_unit(const bf16_t* Qb, int qpitch, const bf16_t* Kb, int kpitch, const bf16_t* Vtb, int vpitch, bf16_t* Ob, int opitch, int q0, int nt, LAS unsigned char* lds, float kbound, const float* qgain, const int* qpos, float qscale) {
;     ...
;                 if (PRIO) {
;                     constexpr int KSN = DQK / 16, NDB = DV / 32;
;                     f32x16 s0 = negm, s1 = negm;
;                     const LAS unsigned char* kb = lds + buf * KBUF + (64 * hf + r) * KS + h * 16;
;                     const LAS unsigned char* vb = lds + VOFF + buf * VBUF + r * VS + h * 8 + 128 * hf;
;                     bf16x8 kf0[KSN], kf1[KSN], vf[4][NDB];
; #pragma unroll
;                     for (int ks = 0; ks < KSN; ++ks) { kf0[ks] = *(const LAS bf16x8*)(kb + ks * 32); kf1[ks] = *(const LAS bf16x8*)(kb + 32 * KS + ks * 32); }
;                     __builtin_amdgcn_sched_barrier(0); __builtin_amdgcn_s_setprio(1); __builtin_amdgcn_sched_barrier(0);
; #pragma unroll
;                     for (int ks = 0; ks < KSN; ++ks) { s0 = MFMA32(kf0[ks], qf[ks], s0); s1 = MFMA32(kf1[ks], qf[ks], s1); }
;                     __builtin_amdgcn_sched_barrier(0); __builtin_amdgcn_s_setprio(0); __builtin_amdgcn_sched_barrier(0);
; #pragma unroll
;                     for (int q4 = 0; q4 < 4; ++q4)
; #pragma unroll
;                         for (int d = 0; d < NDB; ++d) { const LAS unsigned char* vp = vb + d * 32 * VS + q4 * 32;
;                             const s16x4 lo = *(const LAS s16x4*)vp, hi = *(const LAS s16x4*)(vp + 16); vf[q4][d] = (bf16x8){lo[0], lo[1], lo[2], lo[3], hi[0], hi[1], hi[2], hi[3]}; }
;                     if (CAUSAL && key0 + 63 > qlo) {
; #pragma unroll
;                         for (int i = 0; i < 16; ++i) { const int key = key0 + (i & 3) + 8 * (i >> 2) + 4 * h; if (key > qabs) s0[i] = -1e30f; if (key + 32 > qabs) s1[i] = -1e30f; }
.LBB0_1495:
	ds_read_b128 v[2:5], v194
	ds_read_b128 v[6:9], v194 offset:32
	ds_read_b128 v[10:13], v194 offset:6656
	ds_read_b128 v[140:143], v194 offset:6688
	ds_read_b128 v[144:147], v194 offset:64
	ds_read_b128 v[148:151], v194 offset:96
	ds_read_b128 v[152:155], v194 offset:6720
	ds_read_b128 v[156:159], v194 offset:6752
	ds_read_b128 v[198:201], v194 offset:128
	ds_read_b128 v[202:205], v194 offset:160
	ds_read_b128 v[206:209], v194 offset:6784
	ds_read_b128 v[210:213], v194 offset:6816
	global_load_dwordx4 v[96:99], v[172:173], off
	global_load_dwordx4 v[100:103], v[170:171], off
	global_load_dwordx4 v[104:107], v[168:169], off
	global_load_dwordx4 v[108:111], v[166:167], off
	global_load_dwordx4 v[112:115], v[164:165], off
	v_lshl_add_u64 v[164:165], v[164:165], 0, s[14:15]
	v_lshl_add_u64 v[166:167], v[166:167], 0, s[14:15]
	v_lshl_add_u64 v[168:169], v[168:169], 0, s[16:17]
	v_lshl_add_u64 v[170:171], v[170:171], 0, s[16:17]
	v_lshl_add_u64 v[172:173], v[172:173], 0, s[16:17]
	s_setprio 1
	s_setprio 0
	s_cmp_le_i32 s71, s69
	s_waitcnt lgkmcnt(0)
	v_mfma_f32_32x32x16_bf16 v[80:95], v[2:5], v[116:119], v[48:63]
	v_mfma_f32_32x32x16_bf16 v[64:79], v[10:13], v[116:119], v[48:63]
	v_mfma_f32_32x32x16_bf16 v[80:95], v[6:9], v[120:123], v[80:95]
	v_mfma_f32_32x32x16_bf16 v[64:79], v[140:143], v[120:123], v[64:79]
	v_mfma_f32_32x32x16_bf16 v[80:95], v[144:147], v[124:127], v[80:95]
	v_mfma_f32_32x32x16_bf16 v[64:79], v[152:155], v[124:127], v[64:79]
	ds_read_b128 v[152:155], v14
	ds_read_b128 v[140:143], v14 offset:32
	v_mfma_f32_32x32x16_bf16 v[80:95], v[148:151], v[128:131], v[80:95]
	v_mfma_f32_32x32x16_bf16 v[64:79], v[156:159], v[128:131], v[64:79]
	ds_read_b128 v[156:159], v15
	ds_read_b128 v[148:151], v15 offset:32
	ds_read_b128 v[144:147], v14 offset:64
	ds_read_b128 v[10:13], v15 offset:64
	ds_read_b128 v[6:9], v14 offset:96
	ds_read_b128 v[2:5], v15 offset:96
	v_mfma_f32_32x32x16_bf16 v[80:95], v[198:201], v[132:135], v[80:95]
	v_mfma_f32_32x32x16_bf16 v[64:79], v[206:209], v[132:135], v[64:79]
	v_mfma_f32_32x32x16_bf16 v[80:95], v[202:205], v[136:139], v[80:95]
	v_mfma_f32_32x32x16_bf16 v[64:79], v[210:213], v[136:139], v[64:79]
	ds_read_b128 v[214:217], v194 offset:13312
	ds_read_b128 v[218:221], v194 offset:13344
	ds_read_b128 v[222:225], v194 offset:19968
	ds_read_b128 v[226:229], v194 offset:20000
	ds_read_b128 v[230:233], v194 offset:13376
	ds_read_b128 v[234:237], v194 offset:13408
	ds_read_b128 v[238:241], v194 offset:20032
	ds_read_b128 v[242:245], v194 offset:20064
	s_cbranch_scc1 .LBB0_1497
	v_add_u32_e32 v195, s71, v180
	v_subrev_u32_e32 v198, 31, v195
	v_subrev_u32_e32 v197, 63, v195
	v_cmp_le_i32_e32 vcc, v198, v189
	s_nop 6
	v_cndmask_b32_e32 v64, v177, v64, vcc
	v_cmp_lt_i32_e32 vcc, v197, v189
	s_nop 1
	v_cndmask_b32_e32 v81, v177, v81, vcc
	v_cmp_le_i32_e32 vcc, v197, v189
	v_subrev_u32_e32 v197, 30, v195
	s_nop 0
	v_cndmask_b32_e32 v80, v177, v80, vcc
	v_cmp_le_i32_e32 vcc, v197, v189
	v_subrev_u32_e32 v197, 61, v195
	s_nop 0
	v_cndmask_b32_e32 v65, v177, v65, vcc
	v_cmp_le_i32_e32 vcc, v197, v189
	v_subrev_u32_e32 v197, 29, v195
	s_nop 0
	v_cndmask_b32_e32 v82, v177, v82, vcc
	v_cmp_le_i32_e32 vcc, v197, v189
	v_subrev_u32_e32 v197, 60, v195
	s_nop 0
	v_cndmask_b32_e32 v66, v177, v66, vcc
	v_cmp_le_i32_e32 vcc, v197, v189
	v_subrev_u32_e32 v197, 28, v195
	s_nop 0
	v_cndmask_b32_e32 v83, v177, v83, vcc
	v_cmp_le_i32_e32 vcc, v197, v189
	v_subrev_u32_e32 v197, 55, v195
	s_nop 0
	v_cndmask_b32_e32 v67, v177, v67, vcc
	v_cmp_le_i32_e32 vcc, v197, v189
	v_subrev_u32_e32 v197, 23, v195
	s_nop 0
	v_cndmask_b32_e32 v84, v177, v84, vcc
	v_cmp_le_i32_e32 vcc, v197, v189
	v_subrev_u32_e32 v197, 54, v195
	s_nop 0
	v_cndmask_b32_e32 v68, v177, v68, vcc
	v_cmp_le_i32_e32 vcc, v197, v189
	v_subrev_u32_e32 v197, 22, v195
	s_nop 0
	v_cndmask_b32_e32 v85, v177, v85, vcc
	v_cmp_le_i32_e32 vcc, v197, v189
	v_subrev_u32_e32 v197, 53, v195
	s_nop 0
	v_cndmask_b32_e32 v69, v177, v69, vcc
	v_cmp_le_i32_e32 vcc, v197, v189
	v_subrev_u32_e32 v197, 21, v195
	s_nop 0
	v_cndmask_b32_e32 v86, v177, v86, vcc
	v_cmp_le_i32_e32 vcc, v197, v189
	v_subrev_u32_e32 v197, 52, v195
	s_nop 0
	v_cndmask_b32_e32 v70, v177, v70, vcc
	v_cmp_le_i32_e32 vcc, v197, v189
	v_subrev_u32_e32 v197, 20, v195
	s_nop 0
	v_cndmask_b32_e32 v87, v177, v87, vcc
	v_cmp_le_i32_e32 vcc, v197, v189
	v_subrev_u32_e32 v197, 47, v195
	s_nop 0
	v_cndmask_b32_e32 v71, v177, v71, vcc
	v_cmp_le_i32_e32 vcc, v197, v189
	v_add_u32_e32 v197, -15, v195
	s_nop 0
	v_cndmask_b32_e32 v88, v177, v88, vcc
	v_cmp_le_i32_e32 vcc, v197, v189
	v_subrev_u32_e32 v197, 46, v195
	s_nop 0
	v_cndmask_b32_e32 v72, v177, v72, vcc
	v_cmp_le_i32_e32 vcc, v197, v189
	v_add_u32_e32 v197, -14, v195
	s_nop 0
	v_cndmask_b32_e32 v89, v177, v89, vcc
	v_cmp_le_i32_e32 vcc, v197, v189
	v_subrev_u32_e32 v197, 45, v195
	s_nop 0
	v_cndmask_b32_e32 v73, v177, v73, vcc
	v_cmp_le_i32_e32 vcc, v197, v189
	v_add_u32_e32 v197, -13, v195
	s_nop 0
	v_cndmask_b32_e32 v90, v177, v90, vcc
	v_cmp_le_i32_e32 vcc, v197, v189
	v_subrev_u32_e32 v197, 44, v195
	s_nop 0
	v_cndmask_b32_e32 v74, v177, v74, vcc
	v_cmp_le_i32_e32 vcc, v197, v189
	v_add_u32_e32 v197, -12, v195
	s_nop 0
	v_cndmask_b32_e32 v91, v177, v91, vcc
	v_cmp_le_i32_e32 vcc, v197, v189
	v_subrev_u32_e32 v197, 39, v195
	s_nop 0
	v_cndmask_b32_e32 v75, v177, v75, vcc
	v_cmp_le_i32_e32 vcc, v197, v189
	v_add_u32_e32 v197, -7, v195
	s_nop 0
	v_cndmask_b32_e32 v92, v177, v92, vcc
	v_cmp_le_i32_e32 vcc, v197, v189
	v_subrev_u32_e32 v197, 38, v195
	s_nop 0
	v_cndmask_b32_e32 v76, v177, v76, vcc
	v_cmp_le_i32_e32 vcc, v197, v189
	v_add_u32_e32 v197, -6, v195
	s_nop 0
	v_cndmask_b32_e32 v93, v177, v93, vcc
	v_cmp_le_i32_e32 vcc, v197, v189
	v_subrev_u32_e32 v197, 37, v195
	s_nop 0
	v_cndmask_b32_e32 v77, v177, v77, vcc
	v_cmp_le_i32_e32 vcc, v197, v189
	v_add_u32_e32 v197, -5, v195
	s_nop 0
	v_cndmask_b32_e32 v94, v177, v94, vcc
	v_cmp_le_i32_e32 vcc, v197, v189
	v_subrev_u32_e32 v197, 36, v195
	v_add_u32_e32 v195, -4, v195
	v_cndmask_b32_e32 v78, v177, v78, vcc
	v_cmp_le_i32_e32 vcc, v197, v189
	s_nop 1
	v_cndmask_b32_e32 v95, v177, v95, vcc
	v_cmp_le_i32_e32 vcc, v195, v189
	s_nop 1
	v_cndmask_b32_e32 v79, v177, v79, vcc

; DI unsigned pk2(float lo, float hi) { typedef float v2f __attribute__((ext_vector_type(2))); typedef __bf16 v2b __attribute__((ext_vector_type(2))); v2f v = {lo, hi}; v2b b = __builtin_convertvector(v, v2b); return __builtin_bit_cast(unsigned, b); }
; #define MFMA32(a, b, c) __builtin_amdgcn_mfma_f32_32x32x16_bf16((a), (b), (c), 0, 0, 0)
; template <int DQK, int DV, bool CAUSAL, int KT, bool PRIO>
; DI void attn_unit(const bf16_t* Qb, int qpitch, const bf16_t* Kb, int kpitch, const bf16_t* Vtb, int vpitch, bf16_t* Ob, int opitch, int q0, int nt, LAS unsigned char* lds, float kbound, const float* qgain, const int* qpos, float qscale) {
;     ...
;                     float ps = 0.f;
; #pragma unroll
;                     for (int i = 0; i < 16; ++i) { s0[i] = __builtin_amdgcn_exp2f(s0[i]); ps += s0[i]; asm volatile("" : "+v"(ps)); }
; #pragma unroll
;                     for (int i = 0; i < 16; ++i) { s1[i] = __builtin_amdgcn_exp2f(s1[i]); ps += s1[i]; asm volatile("" : "+v"(ps)); }
;                     lrun += ps;
;                     bf16x8 pf[4];
; #pragma unroll
;                     for (int sf = 0; sf < 2; ++sf) {
;                         u32x4 pw; pw.x = pk2(s0[8 * sf], s0[8 * sf + 1]); pw.y = pk2(s0[8 * sf + 2], s0[8 * sf + 3]); pw.z = pk2(s0[8 * sf + 4], s0[8 * sf + 5]); pw.w = pk2(s0[8 * sf + 6], s0[8 * sf + 7]); pf[sf] = __builtin_bit_cast(bf16x8, pw);
;                         u32x4 pv; pv.x = pk2(s1[8 * sf], s1[8 * sf + 1]); pv.y = pk2(s1[8 * sf + 2], s1[8 * sf + 3]); pv.z = pk2(s1[8 * sf + 4], s1[8 * sf + 5]); pv.w = pk2(s1[8 * sf + 6], s1[8 * sf + 7]); pf[2 + sf] = __builtin_bit_cast(bf16x8, pv);
;                     }
;                     __builtin_amdgcn_sched_barrier(0); __builtin_amdgcn_s_setprio(1); __builtin_amdgcn_sched_barrier(0);
; #pragma unroll
;                     for (int q4 = 0; q4 < 4; ++q4)
; #pragma unroll
;                         for (int d = 0; d < NDB; ++d) o[d] = MFMA32(vf[q4][d], pf[q4], o[d]);
;                     __builtin_amdgcn_sched_barrier(0); __builtin_amdgcn_s_setprio(0); __builtin_amdgcn_sched_barrier(0);
.LBB0_1504:
	s_nop 7
	v_exp_f32_e32 v80, v80
	v_exp_f32_e32 v81, v81
	v_exp_f32_e32 v82, v82
	v_exp_f32_e32 v83, v83
	v_add_f32_e32 v195, 0, v80
	v_exp_f32_e32 v84, v84
	v_add_f32_e32 v195, v81, v195
	v_exp_f32_e32 v85, v85
	v_add_f32_e32 v195, v82, v195
	v_exp_f32_e32 v86, v86
	v_add_f32_e32 v195, v83, v195
	v_exp_f32_e32 v87, v87
	v_add_f32_e32 v195, v84, v195
	v_exp_f32_e32 v88, v88
	v_add_f32_e32 v195, v85, v195
	v_exp_f32_e32 v89, v89
	v_add_f32_e32 v195, v86, v195
	v_exp_f32_e32 v90, v90
	v_add_f32_e32 v195, v87, v195
	v_exp_f32_e32 v91, v91
	v_add_f32_e32 v195, v88, v195
	v_exp_f32_e32 v92, v92
	v_add_f32_e32 v195, v89, v195
	v_exp_f32_e32 v93, v93
	v_add_f32_e32 v195, v90, v195
	v_exp_f32_e32 v94, v94
	v_add_f32_e32 v195, v91, v195
	v_exp_f32_e32 v95, v95
	v_add_f32_e32 v195, v92, v195
	v_exp_f32_e32 v197, v64
	v_add_f32_e32 v195, v93, v195
	v_exp_f32_e32 v198, v66
	v_add_f32_e32 v195, v94, v195
	v_exp_f32_e32 v199, v67
	v_add_f32_e32 v64, v95, v195
	v_exp_f32_e32 v195, v65
	v_exp_f32_e32 v200, v68
	v_add_f32_e32 v64, v197, v64
	v_exp_f32_e32 v201, v69
	v_add_f32_e32 v64, v195, v64
	v_exp_f32_e32 v202, v70
	v_add_f32_e32 v64, v198, v64
	v_exp_f32_e32 v71, v71
	v_add_f32_e32 v64, v199, v64
	v_exp_f32_e32 v203, v72
	v_add_f32_e32 v64, v200, v64
	v_exp_f32_e32 v204, v73
	v_add_f32_e32 v64, v201, v64
	v_exp_f32_e32 v205, v74
	v_add_f32_e32 v64, v202, v64
	v_exp_f32_e32 v206, v75
	v_add_f32_e32 v64, v71, v64
	v_exp_f32_e32 v207, v76
	v_add_f32_e32 v64, v203, v64
	v_exp_f32_e32 v208, v77
	v_add_f32_e32 v64, v204, v64
	v_exp_f32_e32 v209, v78
	v_add_f32_e32 v64, v205, v64
	v_exp_f32_e32 v79, v79
	v_add_f32_e32 v64, v206, v64
	v_cvt_pk_bf16_f32 v65, v82, v83
	v_add_f32_e32 v64, v207, v64
	v_cvt_pk_bf16_f32 v66, v84, v85
	v_add_f32_e32 v64, v208, v64
	v_cvt_pk_bf16_f32 v67, v86, v87
	v_add_f32_e32 v64, v209, v64
	v_cvt_pk_bf16_f32 v68, v197, v195
	v_add_f32_e32 v210, v79, v64
	v_cvt_pk_bf16_f32 v64, v80, v81
	v_cvt_pk_bf16_f32 v69, v198, v199
	v_cvt_pk_bf16_f32 v70, v200, v201
	v_cvt_pk_bf16_f32 v71, v202, v71
	v_cvt_pk_bf16_f32 v72, v88, v89
	v_cvt_pk_bf16_f32 v73, v90, v91
	v_cvt_pk_bf16_f32 v74, v92, v93
	v_cvt_pk_bf16_f32 v75, v94, v95
	v_cvt_pk_bf16_f32 v76, v203, v204
	v_cvt_pk_bf16_f32 v77, v205, v206
	v_cvt_pk_bf16_f32 v78, v207, v208
	v_cvt_pk_bf16_f32 v79, v209, v79
	v_add_f32_e32 v0, v0, v210
	s_setprio 1
	s_waitcnt lgkmcnt(0)
	v_mfma_f32_32x32x16_bf16 v[32:47], v[152:155], v[64:67], v[32:47]
	v_mfma_f32_32x32x16_bf16 v[16:31], v[156:159], v[64:67], v[16:31]
	v_mfma_f32_32x32x16_bf16 v[32:47], v[140:143], v[72:75], v[32:47]
	v_mfma_f32_32x32x16_bf16 v[16:31], v[148:151], v[72:75], v[16:31]
	v_mfma_f32_32x32x16_bf16 v[32:47], v[144:147], v[68:71], v[32:47]
	v_mfma_f32_32x32x16_bf16 v[16:31], v[10:13], v[68:71], v[16:31]
	v_mfma_f32_32x32x16_bf16 v[32:47], v[6:9], v[76:79], v[32:47]
	v_mfma_f32_32x32x16_bf16 v[16:31], v[2:5], v[76:79], v[16:31]
	s_setprio 0
	s_add_i32 s12, s71, 1
	s_cmp_gt_i32 s12, s70
	s_cbranch_scc1 .LBB0_1491
; #define LAS __attribute__((address_space(3)))
; #define MFMA32(a, b, c) __builtin_amdgcn_mfma_f32_32x32x16_bf16((a), (b), (c), 0, 0, 0)
; template <int DQK, int DV, bool CAUSAL, int KT, bool PRIO>
; DI void attn_unit(const bf16_t* Qb, int qpitch, const bf16_t* Kb, int kpitch, const bf16_t* Vtb, int vpitch, bf16_t* Ob, int opitch, int q0, int nt, LAS unsigned char* lds, float kbound, const float* qgain, const int* qpos, float qscale) {
;     ...
;             const int key0 = kt * KT + 64 * hf;
;             if (!CAUSAL || key0 <= qlo + 31) {
;                 if (PRIO) {
;                     constexpr int KSN = DQK / 16, NDB = DV / 32;
;                     f32x16 s0 = negm, s1 = negm;
;                     const LAS unsigned char* kb = lds + buf * KBUF + (64 * hf + r) * KS + h * 16;
;                     const LAS unsigned char* vb = lds + VOFF + buf * VBUF + r * VS + h * 8 + 128 * hf;
;                     bf16x8 kf0[KSN], kf1[KSN], vf[4][NDB];
; #pragma unroll
;                     for (int ks = 0; ks < KSN; ++ks) { kf0[ks] = *(const LAS bf16x8*)(kb + ks * 32); kf1[ks] = *(const LAS bf16x8*)(kb + 32 * KS + ks * 32); }
;                     __builtin_amdgcn_sched_barrier(0); __builtin_amdgcn_s_setprio(1); __builtin_amdgcn_sched_barrier(0);
; #pragma unroll
;                     for (int ks = 0; ks < KSN; ++ks) { s0 = MFMA32(kf0[ks], qf[ks], s0); s1 = MFMA32(kf1[ks], qf[ks], s1); }
;                     __builtin_amdgcn_sched_barrier(0); __builtin_amdgcn_s_setprio(0); __builtin_amdgcn_sched_barrier(0);
; #pragma unroll
;                     for (int q4 = 0; q4 < 4; ++q4)
; #pragma unroll
;                         for (int d = 0; d < NDB; ++d) { const LAS unsigned char* vp = vb + d * 32 * VS + q4 * 32;
;                             const s16x4 lo = *(const LAS s16x4*)vp, hi = *(const LAS s16x4*)(vp + 16); vf[q4][d] = (bf16x8){lo[0], lo[1], lo[2], lo[3], hi[0], hi[1], hi[2], hi[3]}; }
;                     if (CAUSAL && key0 + 63 > qlo) {
; #pragma unroll
;                         for (int i = 0; i < 16; ++i) { const int key = key0 + (i & 3) + 8 * (i >> 2) + 4 * h; if (key > qabs) s0[i] = -1e30f; if (key + 32 > qabs) s1[i] = -1e30f; }
.LBB0_1505:
	ds_read_b128 v[198:201], v194 offset:13440
	ds_read_b128 v[202:205], v194 offset:13472
	ds_read_b128 v[206:209], v194 offset:20096
	ds_read_b128 v[210:213], v194 offset:20128
	s_setprio 1
	s_setprio 0
	s_add_i32 s12, s71, 64
	s_cmp_le_i32 s12, s69
	s_waitcnt lgkmcnt(4)
	v_mfma_f32_32x32x16_bf16 v[80:95], v[214:217], v[116:119], v[48:63]
	v_mfma_f32_32x32x16_bf16 v[64:79], v[222:225], v[116:119], v[48:63]
	v_mfma_f32_32x32x16_bf16 v[80:95], v[218:221], v[120:123], v[80:95]
	v_mfma_f32_32x32x16_bf16 v[64:79], v[226:229], v[120:123], v[64:79]
	v_mfma_f32_32x32x16_bf16 v[80:95], v[230:233], v[124:127], v[80:95]
	v_mfma_f32_32x32x16_bf16 v[64:79], v[238:241], v[124:127], v[64:79]
	v_mfma_f32_32x32x16_bf16 v[80:95], v[234:237], v[128:131], v[80:95]
	v_mfma_f32_32x32x16_bf16 v[64:79], v[242:245], v[128:131], v[64:79]
	ds_read_b128 v[156:159], v14 offset:128
	ds_read_b128 v[140:143], v14 offset:160
	ds_read_b128 v[152:155], v15 offset:128
	ds_read_b128 v[148:151], v15 offset:160
	ds_read_b128 v[144:147], v14 offset:192
	ds_read_b128 v[10:13], v15 offset:192
	ds_read_b128 v[6:9], v14 offset:224
	ds_read_b128 v[2:5], v15 offset:224
	s_waitcnt lgkmcnt(8)
	v_mfma_f32_32x32x16_bf16 v[80:95], v[198:201], v[132:135], v[80:95]
	v_mfma_f32_32x32x16_bf16 v[64:79], v[206:209], v[132:135], v[64:79]
	v_mfma_f32_32x32x16_bf16 v[80:95], v[202:205], v[136:139], v[80:95]
	v_mfma_f32_32x32x16_bf16 v[64:79], v[210:213], v[136:139], v[64:79]
	s_cbranch_scc1 .LBB0_1507
	v_add_u32_e32 v14, s71, v180
	v_add_u32_e32 v194, 33, v14
	v_add_u32_e32 v15, 1, v14
	v_cmp_le_i32_e32 vcc, v194, v189
	s_nop 6
	v_cndmask_b32_e32 v64, v177, v64, vcc
	v_cmp_lt_i32_e32 vcc, v15, v189
	s_nop 1
	v_cndmask_b32_e32 v81, v177, v81, vcc
	v_cmp_le_i32_e32 vcc, v15, v189
	v_add_u32_e32 v15, 34, v14
	s_nop 0
	v_cndmask_b32_e32 v80, v177, v80, vcc
	v_cmp_le_i32_e32 vcc, v15, v189
	v_add_u32_e32 v15, 3, v14
	s_nop 0
	v_cndmask_b32_e32 v65, v177, v65, vcc
	v_cmp_le_i32_e32 vcc, v15, v189
	v_add_u32_e32 v15, 35, v14
	s_nop 0
	v_cndmask_b32_e32 v82, v177, v82, vcc
	v_cmp_le_i32_e32 vcc, v15, v189
	v_add_u32_e32 v15, 4, v14
	s_nop 0
	v_cndmask_b32_e32 v66, v177, v66, vcc
	v_cmp_le_i32_e32 vcc, v15, v189
	v_add_u32_e32 v15, 36, v14
	s_nop 0
	v_cndmask_b32_e32 v83, v177, v83, vcc
	v_cmp_le_i32_e32 vcc, v15, v189
	v_add_u32_e32 v15, 9, v14
	s_nop 0
	v_cndmask_b32_e32 v67, v177, v67, vcc
	v_cmp_le_i32_e32 vcc, v15, v189
	v_add_u32_e32 v15, 41, v14
	s_nop 0
	v_cndmask_b32_e32 v84, v177, v84, vcc
	v_cmp_le_i32_e32 vcc, v15, v189
	v_add_u32_e32 v15, 10, v14
	s_nop 0
	v_cndmask_b32_e32 v68, v177, v68, vcc
	v_cmp_le_i32_e32 vcc, v15, v189
	v_add_u32_e32 v15, 42, v14
	s_nop 0
	v_cndmask_b32_e32 v85, v177, v85, vcc
	v_cmp_le_i32_e32 vcc, v15, v189
	v_add_u32_e32 v15, 11, v14
	s_nop 0
	v_cndmask_b32_e32 v69, v177, v69, vcc
	v_cmp_le_i32_e32 vcc, v15, v189
	v_add_u32_e32 v15, 43, v14
	s_nop 0
	v_cndmask_b32_e32 v86, v177, v86, vcc
	v_cmp_le_i32_e32 vcc, v15, v189
	v_add_u32_e32 v15, 12, v14
	s_nop 0
	v_cndmask_b32_e32 v70, v177, v70, vcc
	v_cmp_le_i32_e32 vcc, v15, v189
	v_add_u32_e32 v15, 44, v14
	s_nop 0
	v_cndmask_b32_e32 v87, v177, v87, vcc
	v_cmp_le_i32_e32 vcc, v15, v189
	v_add_u32_e32 v15, 17, v14
	s_nop 0
	v_cndmask_b32_e32 v71, v177, v71, vcc
	v_cmp_le_i32_e32 vcc, v15, v189
	v_add_u32_e32 v15, 49, v14
	s_nop 0
	v_cndmask_b32_e32 v88, v177, v88, vcc
	v_cmp_le_i32_e32 vcc, v15, v189
	v_add_u32_e32 v15, 18, v14
	s_nop 0
	v_cndmask_b32_e32 v72, v177, v72, vcc
	v_cmp_le_i32_e32 vcc, v15, v189
	v_add_u32_e32 v15, 50, v14
	s_nop 0
	v_cndmask_b32_e32 v89, v177, v89, vcc
	v_cmp_le_i32_e32 vcc, v15, v189
	v_add_u32_e32 v15, 19, v14
	s_nop 0
	v_cndmask_b32_e32 v73, v177, v73, vcc
	v_cmp_le_i32_e32 vcc, v15, v189
	v_add_u32_e32 v15, 51, v14
	s_nop 0
	v_cndmask_b32_e32 v90, v177, v90, vcc
	v_cmp_le_i32_e32 vcc, v15, v189
	v_add_u32_e32 v15, 20, v14
	s_nop 0
	v_cndmask_b32_e32 v74, v177, v74, vcc
	v_cmp_le_i32_e32 vcc, v15, v189
	v_add_u32_e32 v15, 52, v14
	s_nop 0
	v_cndmask_b32_e32 v91, v177, v91, vcc
	v_cmp_le_i32_e32 vcc, v15, v189
	v_add_u32_e32 v15, 25, v14
	s_nop 0
	v_cndmask_b32_e32 v75, v177, v75, vcc
	v_cmp_le_i32_e32 vcc, v15, v189
	v_add_u32_e32 v15, 57, v14
	s_nop 0
	v_cndmask_b32_e32 v92, v177, v92, vcc
	v_cmp_le_i32_e32 vcc, v15, v189
	v_add_u32_e32 v15, 26, v14
	s_nop 0
	v_cndmask_b32_e32 v76, v177, v76, vcc
	v_cmp_le_i32_e32 vcc, v15, v189
	v_add_u32_e32 v15, 58, v14
	s_nop 0
	v_cndmask_b32_e32 v93, v177, v93, vcc
	v_cmp_le_i32_e32 vcc, v15, v189
	v_add_u32_e32 v15, 27, v14
	s_nop 0
	v_cndmask_b32_e32 v77, v177, v77, vcc
	v_cmp_le_i32_e32 vcc, v15, v189
	v_add_u32_e32 v15, 59, v14
	s_nop 0
	v_cndmask_b32_e32 v94, v177, v94, vcc
	v_cmp_le_i32_e32 vcc, v15, v189
	v_add_u32_e32 v15, 28, v14
	v_add_u32_e32 v14, 60, v14
	v_cndmask_b32_e32 v78, v177, v78, vcc
	v_cmp_le_i32_e32 vcc, v15, v189
	s_nop 1
	v_cndmask_b32_e32 v95, v177, v95, vcc
	v_cmp_le_i32_e32 vcc, v14, v189
	s_nop 1
	v_cndmask_b32_e32 v79, v177, v79, vcc
